# attention loop: rare blocks (rescale, bias, flag subs) moved out of line so the hot path takes no forward branches
# baseline (speedup 1.0000x reference)
.Lq1_body:
	global_load_dwordx4 v[28:31], v202, s[100:101] offset:-128
	global_load_dwordx4 v[32:35], v202, s[100:101]
	global_load_dwordx4 v[4:7], v203, s[100:101] offset:-128
	global_load_dwordx4 v[12:15], v203, s[100:101]
	ds_read_b128 v[44:47], v214 offset:35840
	ds_read_b128 v[72:75], v214 offset:35904
	ds_read_b128 v[92:95], v214 offset:40192
	ds_read_b128 v[112:115], v214 offset:40256
	ds_read_b128 v[132:135], v214 offset:44544
	ds_read_b128 v[148:151], v214 offset:44608
	ds_read_b128 v[136:139], v214 offset:48896
	ds_read_b128 v[152:155], v214 offset:48960
	s_waitcnt lgkmcnt(7)
	v_mfma_f32_16x16x32_bf16 v[140:143], v[44:47], v[8:11], 0
	v_mfma_f32_16x16x32_bf16 v[44:47], v[44:47], v[20:23], 0
	s_waitcnt lgkmcnt(1)
	v_mfma_f32_16x16x32_bf16 v[156:159], v[92:95], v[8:11], 0
	v_mfma_f32_16x16x32_bf16 v[92:95], v[92:95], v[20:23], 0
	v_mfma_f32_16x16x32_bf16 v[160:163], v[132:135], v[8:11], 0
	v_mfma_f32_16x16x32_bf16 v[132:135], v[132:135], v[20:23], 0
	v_mfma_f32_16x16x32_bf16 v[164:167], v[136:139], v[8:11], 0
	v_mfma_f32_16x16x32_bf16 v[168:171], v[136:139], v[20:23], 0
	v_mfma_f32_16x16x32_bf16 v[144:147], v[72:75], v[16:19], v[140:143]
	v_mfma_f32_16x16x32_bf16 v[136:139], v[72:75], v[24:27], v[44:47]
	v_mfma_f32_16x16x32_bf16 v[44:47], v[112:115], v[16:19], v[156:159]
	v_mfma_f32_16x16x32_bf16 v[92:95], v[112:115], v[24:27], v[92:95]
	v_mfma_f32_16x16x32_bf16 v[140:143], v[148:151], v[16:19], v[160:163]
	v_mfma_f32_16x16x32_bf16 v[132:135], v[148:151], v[24:27], v[132:135]
	s_waitcnt lgkmcnt(0)
	v_mfma_f32_16x16x32_bf16 v[72:75], v[152:155], v[16:19], v[164:167]
	v_mfma_f32_16x16x32_bf16 v[112:115], v[152:155], v[24:27], v[168:171]
	s_cmp_eq_u32 s98, 0
	s_cbranch_scc0 .Lq1_o_subs1
.LBB0_859:
	s_cmp_le_u32 s87, s86
	s_cbranch_scc0 .Lq1_o_bias1
.LBB0_861:
	v_max_f32_e32 v0, v144, v145
	v_max3_f32 v2, v147, v44, v45
	v_max3_f32 v0, v0, v146, v46
	v_max3_f32 v2, v2, v140, v141
	v_max3_f32 v0, v0, v47, v142
	v_max3_f32 v2, v2, v72, v73
	v_max3_f32 v0, v0, v143, v74
	v_max3_f32 v0, v0, v75, v2
	v_max_f32_e32 v2, v136, v137
	v_max3_f32 v3, v139, v92, v93
	v_max3_f32 v2, v2, v138, v94
	v_max3_f32 v3, v3, v132, v133
	v_max3_f32 v2, v2, v95, v134
	v_max3_f32 v3, v3, v112, v113
	v_max3_f32 v2, v2, v135, v114
	v_max3_f32 v2, v2, v115, v3
	v_max_f32_e32 v3, v0, v2
	v_cmp_lt_f32_e32 vcc, s74, v3
	s_cmp_lg_u64 vcc, 0
	s_cselect_b64 s[0:1], -1, 0
	s_cbranch_vccnz .Lq1_o_resc1
.LBB0_863:
	ds_read_b64_tr_b16 v[148:149], v215 offset:17408
	ds_read_b64_tr_b16 v[152:153], v215 offset:17440
	ds_read_b64_tr_b16 v[156:157], v215 offset:17472
	ds_read_b64_tr_b16 v[160:161], v215 offset:17504
	ds_read_b64_tr_b16 v[150:151], v215 offset:22016
	ds_read_b64_tr_b16 v[154:155], v215 offset:22048
	ds_read_b64_tr_b16 v[158:159], v215 offset:22080
	ds_read_b64_tr_b16 v[162:163], v215 offset:22112
	v_exp_f32_e32 v2, v144
	s_waitcnt lgkmcnt(3)
	v_mfma_f32_16x16x32_bf16 v[164:167], v[36:39], v[148:151], v[128:131]
	v_exp_f32_e32 v222, v145
	v_mfma_f32_16x16x32_bf16 v[148:151], v[60:63], v[148:151], v[120:123]
	ds_read_b64_tr_b16 v[238:239], v215 offset:17536
	ds_read_b64_tr_b16 v[242:243], v215 offset:17568
	ds_read_b64_tr_b16 v[246:247], v215 offset:17600
	ds_read_b64_tr_b16 v[250:251], v215 offset:17632
	ds_read_b64_tr_b16 v[240:241], v215 offset:22144
	ds_read_b64_tr_b16 v[244:245], v215 offset:22176
	ds_read_b64_tr_b16 v[248:249], v215 offset:22208
	ds_read_b64_tr_b16 v[252:253], v215 offset:22240
	v_exp_f32_e32 v224, v146
	s_waitcnt lgkmcnt(8)
	v_mfma_f32_16x16x32_bf16 v[124:127], v[36:39], v[152:155], v[124:127]
	v_exp_f32_e32 v122, v147
	v_mfma_f32_16x16x32_bf16 v[152:155], v[60:63], v[152:155], v[108:111]
	v_exp_f32_e32 v226, v44
	v_mfma_f32_16x16x32_bf16 v[116:119], v[36:39], v[156:159], v[116:119]
	v_exp_f32_e32 v110, v45
	v_mfma_f32_16x16x32_bf16 v[168:171], v[60:63], v[156:159], v[100:103]
	v_exp_f32_e32 v228, v46
	v_mfma_f32_16x16x32_bf16 v[104:107], v[36:39], v[160:163], v[104:107]
	v_exp_f32_e32 v100, v47
	v_mfma_f32_16x16x32_bf16 v[160:163], v[60:63], v[160:163], v[96:99]
	v_cvt_pk_bf16_f32 v44, v2, v222
	v_cvt_pk_bf16_f32 v45, v224, v122
	v_cvt_pk_bf16_f32 v46, v226, v110
	v_cvt_pk_bf16_f32 v47, v228, v100
	v_exp_f32_e32 v96, v140
	s_waitcnt lgkmcnt(0)
	v_mfma_f32_16x16x32_bf16 v[180:183], v[36:39], v[238:241], v[88:91]
	v_exp_f32_e32 v230, v141
	v_mfma_f32_16x16x32_bf16 v[184:187], v[60:63], v[238:241], v[76:79]
	v_exp_f32_e32 v232, v142
	v_mfma_f32_16x16x32_bf16 v[80:83], v[36:39], v[242:245], v[80:83]
	v_exp_f32_e32 v78, v143
	v_mfma_f32_16x16x32_bf16 v[188:191], v[60:63], v[242:245], v[64:67]
	ds_read_b64_tr_b16 v[140:141], v215 offset:26624
	ds_read_b64_tr_b16 v[156:157], v215 offset:26656
	ds_read_b64_tr_b16 v[172:173], v215 offset:26688
	ds_read_b64_tr_b16 v[176:177], v215 offset:26720
	ds_read_b64_tr_b16 v[142:143], v215 offset:31232
	ds_read_b64_tr_b16 v[158:159], v215 offset:31264
	ds_read_b64_tr_b16 v[174:175], v215 offset:31296
	ds_read_b64_tr_b16 v[178:179], v215 offset:31328
	v_exp_f32_e32 v234, v72
	v_mfma_f32_16x16x32_bf16 v[68:71], v[36:39], v[246:249], v[68:71]
	v_exp_f32_e32 v66, v73
	v_mfma_f32_16x16x32_bf16 v[192:195], v[60:63], v[246:249], v[52:55]
	v_exp_f32_e32 v236, v74
	v_mfma_f32_16x16x32_bf16 v[56:59], v[36:39], v[250:253], v[56:59]
	v_exp_f32_e32 v54, v75
	v_mfma_f32_16x16x32_bf16 v[48:51], v[60:63], v[250:253], v[48:51]
	v_cvt_pk_bf16_f32 v72, v96, v230
	v_cvt_pk_bf16_f32 v73, v232, v78
	v_cvt_pk_bf16_f32 v74, v234, v66
	v_cvt_pk_bf16_f32 v75, v236, v54
	v_exp_f32_e32 v3, v136
	s_waitcnt lgkmcnt(0)
	v_mfma_f32_16x16x32_bf16 v[144:147], v[40:43], v[140:143], v[164:167]
	v_exp_f32_e32 v223, v137
	v_mfma_f32_16x16x32_bf16 v[140:143], v[84:87], v[140:143], v[148:151]
	ds_read_b64_tr_b16 v[238:239], v215 offset:26752
	ds_read_b64_tr_b16 v[242:243], v215 offset:26784
	ds_read_b64_tr_b16 v[246:247], v215 offset:26816
	ds_read_b64_tr_b16 v[250:251], v215 offset:26848
	ds_read_b64_tr_b16 v[240:241], v215 offset:31360
	ds_read_b64_tr_b16 v[244:245], v215 offset:31392
	ds_read_b64_tr_b16 v[248:249], v215 offset:31424
	ds_read_b64_tr_b16 v[252:253], v215 offset:31456
	v_exp_f32_e32 v225, v138
	v_mfma_f32_16x16x32_bf16 v[148:151], v[40:43], v[156:159], v[124:127]
	v_exp_f32_e32 v123, v139
	v_mfma_f32_16x16x32_bf16 v[136:139], v[84:87], v[156:159], v[152:155]
	v_exp_f32_e32 v227, v92
	v_mfma_f32_16x16x32_bf16 v[156:159], v[40:43], v[172:175], v[116:119]
	v_exp_f32_e32 v111, v93
	v_mfma_f32_16x16x32_bf16 v[152:155], v[84:87], v[172:175], v[168:171]
	v_exp_f32_e32 v229, v94
	v_mfma_f32_16x16x32_bf16 v[164:167], v[40:43], v[176:179], v[104:107]
	v_exp_f32_e32 v101, v95
	v_mfma_f32_16x16x32_bf16 v[160:163], v[84:87], v[176:179], v[160:163]
	s_nop 0
	v_cvt_pk_bf16_f32 v92, v3, v223
	v_cvt_pk_bf16_f32 v93, v225, v123
	v_cvt_pk_bf16_f32 v94, v227, v111
	v_cvt_pk_bf16_f32 v95, v229, v101
	v_exp_f32_e32 v97, v132
	s_waitcnt lgkmcnt(0)
	v_mfma_f32_16x16x32_bf16 v[172:175], v[40:43], v[238:241], v[180:183]
	v_exp_f32_e32 v231, v133
	v_mfma_f32_16x16x32_bf16 v[168:171], v[84:87], v[238:241], v[184:187]
	v_exp_f32_e32 v233, v134
	v_mfma_f32_16x16x32_bf16 v[176:179], v[40:43], v[242:245], v[80:83]
	v_exp_f32_e32 v79, v135
	v_mfma_f32_16x16x32_bf16 v[132:135], v[84:87], v[242:245], v[188:191]
	v_exp_f32_e32 v235, v112
	v_mfma_f32_16x16x32_bf16 v[184:187], v[40:43], v[246:249], v[68:71]
	v_exp_f32_e32 v67, v113
	v_mfma_f32_16x16x32_bf16 v[180:183], v[84:87], v[246:249], v[192:195]
	v_exp_f32_e32 v237, v114
	v_mfma_f32_16x16x32_bf16 v[192:195], v[40:43], v[250:253], v[56:59]
	v_exp_f32_e32 v55, v115
	v_mfma_f32_16x16x32_bf16 v[188:191], v[84:87], v[250:253], v[48:51]
	s_andn2_b64 vcc, exec, s[0:1]
	s_cbranch_vccz .Lq1_o_post1

.Lq1_h2_nok:
	global_load_dwordx4 v[4:7], v203, s[100:101] offset:-128
	global_load_dwordx4 v[12:15], v203, s[100:101]
	s_cmp_ge_u32 s89, s83
	s_cbranch_scc1 .Lq1_h2_pvonly
	ds_read_b128 v[36:39], v214
	ds_read_b128 v[40:43], v214 offset:64
	ds_read_b128 v[60:63], v214 offset:4352
	ds_read_b128 v[84:87], v214 offset:4416
	ds_read_b128 v[64:67], v214 offset:8704
	ds_read_b128 v[124:127], v214 offset:8768
	ds_read_b128 v[108:111], v214 offset:13056
	ds_read_b128 v[100:103], v214 offset:13120
	s_waitcnt lgkmcnt(7)
	v_mfma_f32_16x16x32_bf16 v[120:123], v[36:39], v[8:11], 0
	v_mfma_f32_16x16x32_bf16 v[36:39], v[36:39], v[20:23], 0
	s_waitcnt lgkmcnt(1)
	v_mfma_f32_16x16x32_bf16 v[116:119], v[60:63], v[8:11], 0
	v_mfma_f32_16x16x32_bf16 v[60:63], v[60:63], v[20:23], 0
	v_mfma_f32_16x16x32_bf16 v[96:99], v[64:67], v[8:11], 0
	v_mfma_f32_16x16x32_bf16 v[64:67], v[64:67], v[20:23], 0
	v_mfma_f32_16x16x32_bf16 v[104:107], v[108:111], v[8:11], 0
	v_mfma_f32_16x16x32_bf16 v[76:79], v[108:111], v[20:23], 0
	v_mfma_f32_16x16x32_bf16 v[128:131], v[40:43], v[16:19], v[120:123]
	v_mfma_f32_16x16x32_bf16 v[108:111], v[40:43], v[24:27], v[36:39]
	v_mfma_f32_16x16x32_bf16 v[36:39], v[84:87], v[16:19], v[116:119]
	v_mfma_f32_16x16x32_bf16 v[60:63], v[84:87], v[24:27], v[60:63]
	v_mfma_f32_16x16x32_bf16 v[120:123], v[124:127], v[16:19], v[96:99]
	v_mfma_f32_16x16x32_bf16 v[64:67], v[124:127], v[24:27], v[64:67]
	s_waitcnt lgkmcnt(0)
	v_mfma_f32_16x16x32_bf16 v[40:43], v[100:103], v[16:19], v[104:107]
	v_mfma_f32_16x16x32_bf16 v[84:87], v[100:103], v[24:27], v[76:79]
	s_cmp_eq_u32 s98, 0
	s_cbranch_scc0 .Lq1_o_subs2
.LBB0_875:
	s_add_i32 s2, s87, 64
	s_cmp_le_u32 s2, s86
	s_cbranch_scc0 .Lq1_o_bias2
.LBB0_877:
	v_max_f32_e32 v0, v128, v129
	v_max3_f32 v2, v131, v36, v37
	v_max3_f32 v0, v0, v130, v38
	v_max3_f32 v2, v2, v120, v121
	v_max3_f32 v0, v0, v39, v122
	v_max3_f32 v2, v2, v40, v41
	v_max3_f32 v0, v0, v123, v42
	v_max3_f32 v0, v0, v43, v2
	v_max_f32_e32 v2, v108, v109
	v_max3_f32 v3, v111, v60, v61
	v_max3_f32 v2, v2, v110, v62
	v_max3_f32 v3, v3, v64, v65
	v_max3_f32 v2, v2, v63, v66
	v_max3_f32 v3, v3, v84, v85
	v_max3_f32 v2, v2, v67, v86
	v_max3_f32 v2, v2, v87, v3
	v_max_f32_e32 v3, v0, v2
	v_cmp_lt_f32_e32 vcc, s74, v3
	s_cmp_lg_u64 vcc, 0
	s_cselect_b64 s[2:3], -1, 0
	s_cbranch_vccnz .Lq1_o_resc2
.LBB0_879:
	ds_read_b64_tr_b16 v[124:125], v215 offset:53248
	ds_read_b64_tr_b16 v[100:101], v215 offset:53280
	ds_read_b64_tr_b16 v[116:117], v215 offset:53312
	ds_read_b64_tr_b16 v[96:97], v215 offset:53344
	ds_read_b64_tr_b16 v[126:127], v215 offset:57856
	ds_read_b64_tr_b16 v[102:103], v215 offset:57888
	ds_read_b64_tr_b16 v[118:119], v215 offset:57920
	ds_read_b64_tr_b16 v[98:99], v215 offset:57952
	v_exp_f32_e32 v2, v128
	s_waitcnt lgkmcnt(3)
	v_mfma_f32_16x16x32_bf16 v[104:107], v[44:47], v[124:127], v[144:147]
	v_exp_f32_e32 v222, v129
	v_mfma_f32_16x16x32_bf16 v[124:127], v[92:95], v[124:127], v[140:143]
	ds_read_b64_tr_b16 v[238:239], v215 offset:53376
	ds_read_b64_tr_b16 v[242:243], v215 offset:53408
	ds_read_b64_tr_b16 v[246:247], v215 offset:53440
	ds_read_b64_tr_b16 v[250:251], v215 offset:53472
	ds_read_b64_tr_b16 v[240:241], v215 offset:57984
	ds_read_b64_tr_b16 v[244:245], v215 offset:58016
	ds_read_b64_tr_b16 v[248:249], v215 offset:58048
	ds_read_b64_tr_b16 v[252:253], v215 offset:58080
	v_exp_f32_e32 v224, v130
	s_waitcnt lgkmcnt(8)
	v_mfma_f32_16x16x32_bf16 v[148:151], v[44:47], v[100:103], v[148:151]
	v_exp_f32_e32 v142, v131
	v_mfma_f32_16x16x32_bf16 v[100:103], v[92:95], v[100:103], v[136:139]
	v_exp_f32_e32 v226, v36
	v_mfma_f32_16x16x32_bf16 v[156:159], v[44:47], v[116:119], v[156:159]
	v_exp_f32_e32 v138, v37
	v_mfma_f32_16x16x32_bf16 v[76:79], v[92:95], v[116:119], v[152:155]
	v_exp_f32_e32 v228, v38
	v_mfma_f32_16x16x32_bf16 v[164:167], v[44:47], v[96:99], v[164:167]
	v_exp_f32_e32 v154, v39
	v_mfma_f32_16x16x32_bf16 v[96:99], v[92:95], v[96:99], v[160:163]
	v_cvt_pk_bf16_f32 v36, v2, v222
	v_cvt_pk_bf16_f32 v37, v224, v142
	v_cvt_pk_bf16_f32 v38, v226, v138
	v_cvt_pk_bf16_f32 v39, v228, v154
	v_exp_f32_e32 v160, v120
	s_waitcnt lgkmcnt(0)
	v_mfma_f32_16x16x32_bf16 v[52:55], v[44:47], v[238:241], v[172:175]
	v_exp_f32_e32 v230, v121
	v_mfma_f32_16x16x32_bf16 v[68:71], v[92:95], v[238:241], v[168:171]
	v_exp_f32_e32 v232, v122
	v_mfma_f32_16x16x32_bf16 v[176:179], v[44:47], v[242:245], v[176:179]
	v_exp_f32_e32 v170, v123
	v_mfma_f32_16x16x32_bf16 v[48:51], v[92:95], v[242:245], v[132:135]
	ds_read_b64_tr_b16 v[120:121], v215 offset:62464
	ds_read_b64_tr_b16 v[116:117], v215 offset:62496
	ds_read_b64_tr_b16 v[88:89], v215 offset:62528
	ds_read_b64_tr_b16 v[80:81], v215 offset:62560
	ds_read_b64_tr_b16 v[122:123], v216 offset:13824
	ds_read_b64_tr_b16 v[118:119], v216 offset:13856
	ds_read_b64_tr_b16 v[90:91], v216 offset:13888
	ds_read_b64_tr_b16 v[82:83], v216 offset:13920
	v_exp_f32_e32 v234, v40
	v_mfma_f32_16x16x32_bf16 v[184:187], v[44:47], v[246:249], v[184:187]
	v_exp_f32_e32 v134, v41
	v_mfma_f32_16x16x32_bf16 v[56:59], v[92:95], v[246:249], v[180:183]
	v_exp_f32_e32 v236, v42
	v_mfma_f32_16x16x32_bf16 v[192:195], v[44:47], v[250:253], v[192:195]
	v_exp_f32_e32 v182, v43
	v_mfma_f32_16x16x32_bf16 v[188:191], v[92:95], v[250:253], v[188:191]
	v_cvt_pk_bf16_f32 v40, v160, v230
	v_cvt_pk_bf16_f32 v41, v232, v170
	v_cvt_pk_bf16_f32 v42, v234, v134
	v_cvt_pk_bf16_f32 v43, v236, v182
	v_exp_f32_e32 v3, v108
	s_waitcnt lgkmcnt(0)
	v_mfma_f32_16x16x32_bf16 v[128:131], v[72:75], v[120:123], v[104:107]
	v_exp_f32_e32 v223, v109
	v_mfma_f32_16x16x32_bf16 v[120:123], v[112:115], v[120:123], v[124:127]
	ds_read_b64_tr_b16 v[238:239], v215 offset:62592
	ds_read_b64_tr_b16 v[242:243], v215 offset:62624
	ds_read_b64_tr_b16 v[246:247], v215 offset:62656
	ds_read_b64_tr_b16 v[250:251], v215 offset:62688
	ds_read_b64_tr_b16 v[240:241], v216 offset:13952
	ds_read_b64_tr_b16 v[244:245], v216 offset:13984
	ds_read_b64_tr_b16 v[248:249], v216 offset:14016
	ds_read_b64_tr_b16 v[252:253], v216 offset:14048
	v_exp_f32_e32 v225, v110
	v_mfma_f32_16x16x32_bf16 v[124:127], v[72:75], v[116:119], v[148:151]
	v_exp_f32_e32 v143, v111
	v_mfma_f32_16x16x32_bf16 v[108:111], v[112:115], v[116:119], v[100:103]
	v_exp_f32_e32 v227, v60
	v_mfma_f32_16x16x32_bf16 v[116:119], v[72:75], v[88:91], v[156:159]
	v_exp_f32_e32 v139, v61
	v_mfma_f32_16x16x32_bf16 v[100:103], v[112:115], v[88:91], v[76:79]
	v_exp_f32_e32 v229, v62
	v_mfma_f32_16x16x32_bf16 v[104:107], v[72:75], v[80:83], v[164:167]
	v_exp_f32_e32 v155, v63
	v_mfma_f32_16x16x32_bf16 v[96:99], v[112:115], v[80:83], v[96:99]
	s_nop 0
	v_cvt_pk_bf16_f32 v60, v3, v223
	v_cvt_pk_bf16_f32 v61, v225, v143
	v_cvt_pk_bf16_f32 v62, v227, v139
	v_cvt_pk_bf16_f32 v63, v229, v155
	v_exp_f32_e32 v161, v64
	s_waitcnt lgkmcnt(0)
	v_mfma_f32_16x16x32_bf16 v[88:91], v[72:75], v[238:241], v[52:55]
	v_exp_f32_e32 v231, v65
	v_mfma_f32_16x16x32_bf16 v[76:79], v[112:115], v[238:241], v[68:71]
	v_exp_f32_e32 v233, v66
	v_mfma_f32_16x16x32_bf16 v[80:83], v[72:75], v[242:245], v[176:179]
	v_exp_f32_e32 v171, v67
	v_mfma_f32_16x16x32_bf16 v[64:67], v[112:115], v[242:245], v[48:51]
	v_exp_f32_e32 v235, v84
	v_mfma_f32_16x16x32_bf16 v[68:71], v[72:75], v[246:249], v[184:187]
	v_exp_f32_e32 v135, v85
	v_mfma_f32_16x16x32_bf16 v[52:55], v[112:115], v[246:249], v[56:59]
	v_exp_f32_e32 v237, v86
	v_mfma_f32_16x16x32_bf16 v[56:59], v[72:75], v[250:253], v[192:195]
	v_exp_f32_e32 v183, v87
	v_mfma_f32_16x16x32_bf16 v[48:51], v[112:115], v[250:253], v[188:191]
	s_andn2_b64 vcc, exec, s[2:3]
	s_cbranch_vccz .Lq1_o_post2

.Lq1_o_subs1:
	v_sub_f32_e32 v147, v147, v196
	v_sub_f32_e32 v146, v146, v196
	v_sub_f32_e32 v145, v145, v196
	v_sub_f32_e32 v144, v144, v196
	v_sub_f32_e32 v47, v47, v196
	v_sub_f32_e32 v46, v46, v196
	v_sub_f32_e32 v45, v45, v196
	v_sub_f32_e32 v44, v44, v196
	v_sub_f32_e32 v143, v143, v196
	v_sub_f32_e32 v142, v142, v196
	v_sub_f32_e32 v141, v141, v196
	v_sub_f32_e32 v140, v140, v196
	v_sub_f32_e32 v75, v75, v196
	v_sub_f32_e32 v74, v74, v196
	v_sub_f32_e32 v73, v73, v196
	v_sub_f32_e32 v72, v72, v196
	v_sub_f32_e32 v139, v139, v197
	v_sub_f32_e32 v138, v138, v197
	v_sub_f32_e32 v137, v137, v197
	v_sub_f32_e32 v136, v136, v197
	v_sub_f32_e32 v95, v95, v197
	v_sub_f32_e32 v94, v94, v197
	v_sub_f32_e32 v93, v93, v197
	v_sub_f32_e32 v92, v92, v197
	v_sub_f32_e32 v135, v135, v197
	v_sub_f32_e32 v134, v134, v197
	v_sub_f32_e32 v133, v133, v197
	v_sub_f32_e32 v132, v132, v197
	v_sub_f32_e32 v115, v115, v197
	v_sub_f32_e32 v114, v114, v197
	v_sub_f32_e32 v113, v113, v197
	v_sub_f32_e32 v112, v112, v197
	s_branch .LBB0_859
.Lq1_o_bias1:
	v_add_u32_e32 v0, s87, v217
	v_add_u32_e32 v154, 0x80, v0
	v_max_i32_e32 v3, -1, v154
	v_max_i32_e32 v148, -2, v154
	v_max_i32_e32 v149, -3, v154
	v_max_i32_e32 v150, -16, v154
	v_max_i32_e32 v151, 0xffffffef, v154
	v_max_i32_e32 v152, 0xffffffee, v154
	v_max_i32_e32 v153, 0xffffffed, v154
	v_add_u32_e32 v3, 1, v3
	v_add_u32_e32 v148, 2, v148
	v_add_u32_e32 v149, 3, v149
	v_add_u32_e32 v150, 16, v150
	v_add_u32_e32 v151, 17, v151
	v_add_u32_e32 v152, 18, v152
	v_add_u32_e32 v153, 19, v153
	v_med3_i32 v2, v154, 0, v209
	v_min_u32_e32 v3, 0xff, v3
	v_min_u32_e32 v148, 0xff, v148
	v_min_u32_e32 v149, 0xff, v149
	v_min_u32_e32 v150, 0xff, v150
	v_min_u32_e32 v151, 0xff, v151
	v_min_u32_e32 v152, 0xff, v152
	v_min_u32_e32 v153, 0xff, v153
	v_lshl_add_u32 v2, v2, 2, s71
	v_lshl_add_u32 v3, v3, 2, s71
	v_lshl_add_u32 v148, v148, 2, s71
	v_lshl_add_u32 v149, v149, 2, s71
	v_lshl_add_u32 v150, v150, 2, s71
	v_lshl_add_u32 v151, v151, 2, s71
	v_lshl_add_u32 v152, v152, 2, s71
	v_lshl_add_u32 v153, v153, 2, s71
	ds_read_b32 v2, v2
	ds_read_b32 v3, v3
	ds_read_b32 v148, v148
	ds_read_b32 v149, v149
	ds_read_b32 v150, v150
	ds_read_b32 v151, v151
	ds_read_b32 v152, v152
	ds_read_b32 v153, v153
	s_waitcnt lgkmcnt(4)
	v_pk_add_f32 v[146:147], v[146:147], v[148:149]
	v_pk_add_f32 v[144:145], v[144:145], v[2:3]
	v_max_i32_e32 v2, 0xffffffe0, v154
	v_max_i32_e32 v3, 0xffffffdf, v154
	v_max_i32_e32 v148, 0xffffffde, v154
	v_max_i32_e32 v149, 0xffffffdd, v154
	v_max_i32_e32 v155, 0xffffffd0, v154
	v_max_i32_e32 v156, 0xffffffcf, v154
	v_max_i32_e32 v157, 0xffffffce, v154
	v_add_u32_e32 v2, 32, v2
	v_add_u32_e32 v3, 33, v3
	v_add_u32_e32 v148, 34, v148
	v_add_u32_e32 v149, 35, v149
	v_add_u32_e32 v155, 48, v155
	v_add_u32_e32 v156, 49, v156
	v_add_u32_e32 v157, 50, v157
	v_max_i32_e32 v154, 0xffffffcd, v154
	v_min_u32_e32 v2, 0xff, v2
	v_min_u32_e32 v3, 0xff, v3
	v_min_u32_e32 v148, 0xff, v148
	v_min_u32_e32 v149, 0xff, v149
	v_min_u32_e32 v155, 0xff, v155
	v_min_u32_e32 v156, 0xff, v156
	v_min_u32_e32 v157, 0xff, v157
	v_add_u32_e32 v154, 51, v154
	v_lshl_add_u32 v2, v2, 2, s71
	v_lshl_add_u32 v3, v3, 2, s71
	v_lshl_add_u32 v148, v148, 2, s71
	v_lshl_add_u32 v149, v149, 2, s71
	v_lshl_add_u32 v155, v155, 2, s71
	v_lshl_add_u32 v156, v156, 2, s71
	v_lshl_add_u32 v157, v157, 2, s71
	v_min_u32_e32 v154, 0xff, v154
	v_lshl_add_u32 v158, v154, 2, s71
	ds_read_b32 v2, v2
	ds_read_b32 v3, v3
	ds_read_b32 v148, v148
	ds_read_b32 v149, v149
	ds_read_b32 v154, v155
	ds_read_b32 v155, v156
	ds_read_b32 v156, v157
	ds_read_b32 v157, v158
	v_add_u32_e32 v0, 0x70, v0
	s_waitcnt lgkmcnt(8)
	v_pk_add_f32 v[46:47], v[46:47], v[152:153]
	v_pk_add_f32 v[44:45], v[44:45], v[150:151]
	s_waitcnt lgkmcnt(4)
	v_pk_add_f32 v[142:143], v[142:143], v[148:149]
	v_pk_add_f32 v[140:141], v[140:141], v[2:3]
	v_max_i32_e32 v3, -1, v0
	v_max_i32_e32 v148, -2, v0
	v_max_i32_e32 v149, -3, v0
	v_max_i32_e32 v150, -16, v0
	v_max_i32_e32 v151, 0xffffffef, v0
	v_max_i32_e32 v152, 0xffffffee, v0
	v_max_i32_e32 v153, 0xffffffed, v0
	v_add_u32_e32 v3, 1, v3
	v_add_u32_e32 v148, 2, v148
	v_add_u32_e32 v149, 3, v149
	v_add_u32_e32 v150, 16, v150
	v_add_u32_e32 v151, 17, v151
	v_add_u32_e32 v152, 18, v152
	v_add_u32_e32 v153, 19, v153
	v_med3_i32 v2, v0, 0, v209
	v_min_u32_e32 v3, 0xff, v3
	v_min_u32_e32 v148, 0xff, v148
	v_min_u32_e32 v149, 0xff, v149
	v_min_u32_e32 v150, 0xff, v150
	v_min_u32_e32 v151, 0xff, v151
	v_min_u32_e32 v152, 0xff, v152
	v_min_u32_e32 v153, 0xff, v153
	v_lshl_add_u32 v2, v2, 2, s71
	v_lshl_add_u32 v3, v3, 2, s71
	v_lshl_add_u32 v148, v148, 2, s71
	v_lshl_add_u32 v149, v149, 2, s71
	v_lshl_add_u32 v150, v150, 2, s71
	v_lshl_add_u32 v151, v151, 2, s71
	v_lshl_add_u32 v152, v152, 2, s71
	v_lshl_add_u32 v153, v153, 2, s71
	ds_read_b32 v2, v2
	ds_read_b32 v3, v3
	ds_read_b32 v148, v148
	ds_read_b32 v149, v149
	ds_read_b32 v150, v150
	ds_read_b32 v151, v151
	ds_read_b32 v152, v152
	ds_read_b32 v153, v153
	s_waitcnt lgkmcnt(8)
	v_pk_add_f32 v[74:75], v[74:75], v[156:157]
	v_pk_add_f32 v[72:73], v[72:73], v[154:155]
	s_waitcnt lgkmcnt(4)
	v_pk_add_f32 v[138:139], v[138:139], v[148:149]
	v_pk_add_f32 v[136:137], v[136:137], v[2:3]
	v_max_i32_e32 v2, 0xffffffe0, v0
	v_max_i32_e32 v3, 0xffffffdf, v0
	v_max_i32_e32 v148, 0xffffffde, v0
	v_max_i32_e32 v149, 0xffffffdd, v0
	v_max_i32_e32 v154, 0xffffffd0, v0
	v_max_i32_e32 v155, 0xffffffcf, v0
	v_max_i32_e32 v156, 0xffffffce, v0
	v_add_u32_e32 v2, 32, v2
	v_add_u32_e32 v3, 33, v3
	v_add_u32_e32 v148, 34, v148
	v_add_u32_e32 v149, 35, v149
	v_add_u32_e32 v154, 48, v154
	v_add_u32_e32 v155, 49, v155
	v_add_u32_e32 v156, 50, v156
	v_max_i32_e32 v0, 0xffffffcd, v0
	v_min_u32_e32 v2, 0xff, v2
	v_min_u32_e32 v3, 0xff, v3
	v_min_u32_e32 v148, 0xff, v148
	v_min_u32_e32 v149, 0xff, v149
	v_min_u32_e32 v154, 0xff, v154
	v_min_u32_e32 v155, 0xff, v155
	v_min_u32_e32 v156, 0xff, v156
	v_add_u32_e32 v0, 51, v0
	v_lshl_add_u32 v2, v2, 2, s71
	v_lshl_add_u32 v3, v3, 2, s71
	v_lshl_add_u32 v148, v148, 2, s71
	v_lshl_add_u32 v149, v149, 2, s71
	v_lshl_add_u32 v154, v154, 2, s71
	v_lshl_add_u32 v155, v155, 2, s71
	v_lshl_add_u32 v156, v156, 2, s71
	v_min_u32_e32 v0, 0xff, v0
	v_lshl_add_u32 v0, v0, 2, s71
	ds_read_b32 v2, v2
	ds_read_b32 v3, v3
	ds_read_b32 v148, v148
	ds_read_b32 v149, v149
	ds_read_b32 v154, v154
	ds_read_b32 v155, v155
	ds_read_b32 v156, v156
	ds_read_b32 v157, v0
	s_waitcnt lgkmcnt(8)
	v_pk_add_f32 v[94:95], v[94:95], v[152:153]
	v_pk_add_f32 v[92:93], v[92:93], v[150:151]
	s_waitcnt lgkmcnt(4)
	v_pk_add_f32 v[134:135], v[134:135], v[148:149]
	v_pk_add_f32 v[132:133], v[132:133], v[2:3]
	s_waitcnt lgkmcnt(0)
	v_pk_add_f32 v[114:115], v[114:115], v[156:157]
	v_pk_add_f32 v[112:113], v[112:113], v[154:155]
	s_branch .LBB0_861
.Lq1_o_resc1:
	s_mov_b32 s98, 1
	v_and_b32_e32 v148, 64, v212
	v_xor_b32_e32 v3, 16, v212
	v_add_u32_e32 v148, 64, v148
	v_cmp_lt_i32_e32 vcc, v3, v148
	v_xor_b32_e32 v149, 32, v212
	s_nop 0
	v_cndmask_b32_e32 v3, v212, v3, vcc
	v_lshlrev_b32_e32 v3, 2, v3
	ds_bpermute_b32 v150, v3, v0
	ds_bpermute_b32 v3, v3, v2
	v_cmp_lt_i32_e32 vcc, v149, v148
	v_max_f32_e32 v2, v2, v2
	v_max_f32_e32 v0, v0, v0
	v_cndmask_b32_e32 v148, v212, v149, vcc
	s_waitcnt lgkmcnt(0)
	v_max_f32_e32 v3, v3, v3
	v_lshlrev_b32_e32 v148, 2, v148
	v_max_f32_e32 v149, v150, v150
	v_max_f32_e32 v2, v2, v3
	v_max_f32_e32 v0, v0, v149
	ds_bpermute_b32 v3, v148, v2
	ds_bpermute_b32 v149, v148, v0
	s_waitcnt lgkmcnt(1)
	v_max_f32_e32 v3, v3, v3
	s_waitcnt lgkmcnt(0)
	v_max_f32_e32 v148, v149, v149
	v_max_f32_e32 v2, v2, v3
	v_max_f32_e32 v0, v0, v148
	v_cmp_lt_f32_e32 vcc, s74, v2
	s_nop 1
	v_cndmask_b32_e32 v3, 0, v2, vcc
	v_cmp_lt_f32_e32 vcc, s74, v0
	v_exp_f32_e64 v201, -v3
	v_sub_f32_e32 v136, v136, v3
	v_cndmask_b32_e32 v2, 0, v0, vcc
	v_exp_f32_e64 v200, -v2
	v_sub_f32_e32 v144, v144, v2
	v_sub_f32_e32 v145, v145, v2
	v_sub_f32_e32 v146, v146, v2
	v_sub_f32_e32 v147, v147, v2
	v_sub_f32_e32 v44, v44, v2
	v_sub_f32_e32 v45, v45, v2
	v_sub_f32_e32 v46, v46, v2
	v_sub_f32_e32 v47, v47, v2
	v_sub_f32_e32 v140, v140, v2
	v_sub_f32_e32 v141, v141, v2
	v_sub_f32_e32 v142, v142, v2
	v_sub_f32_e32 v143, v143, v2
	v_sub_f32_e32 v72, v72, v2
	v_sub_f32_e32 v73, v73, v2
	v_sub_f32_e32 v74, v74, v2
	v_sub_f32_e32 v75, v75, v2
	v_pk_add_f32 v[196:197], v[196:197], v[2:3]
	v_sub_f32_e32 v137, v137, v3
	v_sub_f32_e32 v138, v138, v3
	v_sub_f32_e32 v139, v139, v3
	v_sub_f32_e32 v92, v92, v3
	v_sub_f32_e32 v93, v93, v3
	v_sub_f32_e32 v94, v94, v3
	v_sub_f32_e32 v95, v95, v3
	v_sub_f32_e32 v132, v132, v3
	v_sub_f32_e32 v133, v133, v3
	v_sub_f32_e32 v134, v134, v3
	v_sub_f32_e32 v135, v135, v3
	v_sub_f32_e32 v112, v112, v3
	v_sub_f32_e32 v113, v113, v3
	v_sub_f32_e32 v114, v114, v3
	v_sub_f32_e32 v115, v115, v3
	v_pk_mul_f32 v[198:199], v[198:199], v[200:201]
	s_branch .LBB0_863
.Lq1_o_post1:
	v_mov_b32_e32 v0, v210
	s_nop 0
	v_lshlrev_b32_e32 v0, 2, v0
	v_and_b32_e32 v0, 60, v0
	v_and_or_b32 v0, v212, 64, v0
	v_lshlrev_b32_e32 v0, 2, v0
	ds_bpermute_b32 v48, v0, v200
	ds_bpermute_b32 v50, v0, v200 offset:8
	ds_bpermute_b32 v51, v0, v200 offset:12
	ds_bpermute_b32 v49, v0, v200 offset:4
	ds_bpermute_b32 v56, v0, v201
	ds_bpermute_b32 v58, v0, v201 offset:8
	ds_bpermute_b32 v59, v0, v201 offset:12
	ds_bpermute_b32 v57, v0, v201 offset:4
	s_waitcnt lgkmcnt(5)
	v_pk_mul_f32 v[146:147], v[146:147], v[50:51]
	s_waitcnt lgkmcnt(4)
	v_pk_mul_f32 v[144:145], v[144:145], v[48:49]
	v_pk_mul_f32 v[150:151], v[150:151], v[50:51]
	v_pk_mul_f32 v[148:149], v[148:149], v[48:49]
	v_pk_mul_f32 v[158:159], v[158:159], v[50:51]
	v_pk_mul_f32 v[156:157], v[156:157], v[48:49]
	v_pk_mul_f32 v[166:167], v[166:167], v[50:51]
	v_pk_mul_f32 v[164:165], v[164:165], v[48:49]
	v_pk_mul_f32 v[174:175], v[174:175], v[50:51]
	v_pk_mul_f32 v[172:173], v[172:173], v[48:49]
	v_pk_mul_f32 v[178:179], v[178:179], v[50:51]
	v_pk_mul_f32 v[176:177], v[176:177], v[48:49]
	v_pk_mul_f32 v[186:187], v[186:187], v[50:51]
	v_pk_mul_f32 v[184:185], v[184:185], v[48:49]
	v_pk_mul_f32 v[194:195], v[194:195], v[50:51]
	v_pk_mul_f32 v[192:193], v[192:193], v[48:49]
	s_waitcnt lgkmcnt(1)
	v_pk_mul_f32 v[142:143], v[142:143], v[58:59]
	s_waitcnt lgkmcnt(0)
	v_pk_mul_f32 v[140:141], v[140:141], v[56:57]
	v_pk_mul_f32 v[138:139], v[138:139], v[58:59]
	v_pk_mul_f32 v[136:137], v[136:137], v[56:57]
	v_pk_mul_f32 v[154:155], v[154:155], v[58:59]
	v_pk_mul_f32 v[152:153], v[152:153], v[56:57]
	v_pk_mul_f32 v[162:163], v[162:163], v[58:59]
	v_pk_mul_f32 v[160:161], v[160:161], v[56:57]
	v_pk_mul_f32 v[170:171], v[170:171], v[58:59]
	v_pk_mul_f32 v[168:169], v[168:169], v[56:57]
	v_pk_mul_f32 v[134:135], v[134:135], v[58:59]
	v_pk_mul_f32 v[132:133], v[132:133], v[56:57]
	v_pk_mul_f32 v[182:183], v[182:183], v[58:59]
	v_pk_mul_f32 v[180:181], v[180:181], v[56:57]
	v_pk_mul_f32 v[190:191], v[190:191], v[58:59]
	v_pk_mul_f32 v[188:189], v[188:189], v[56:57]
	s_branch .LBB0_865
.Lq1_o_subs2:
	v_sub_f32_e32 v131, v131, v196
	v_sub_f32_e32 v130, v130, v196
	v_sub_f32_e32 v129, v129, v196
	v_sub_f32_e32 v128, v128, v196
	v_sub_f32_e32 v39, v39, v196
	v_sub_f32_e32 v38, v38, v196
	v_sub_f32_e32 v37, v37, v196
	v_sub_f32_e32 v36, v36, v196
	v_sub_f32_e32 v123, v123, v196
	v_sub_f32_e32 v122, v122, v196
	v_sub_f32_e32 v121, v121, v196
	v_sub_f32_e32 v120, v120, v196
	v_sub_f32_e32 v43, v43, v196
	v_sub_f32_e32 v42, v42, v196
	v_sub_f32_e32 v41, v41, v196
	v_sub_f32_e32 v40, v40, v196
	v_sub_f32_e32 v111, v111, v197
	v_sub_f32_e32 v110, v110, v197
	v_sub_f32_e32 v109, v109, v197
	v_sub_f32_e32 v108, v108, v197
	v_sub_f32_e32 v63, v63, v197
	v_sub_f32_e32 v62, v62, v197
	v_sub_f32_e32 v61, v61, v197
	v_sub_f32_e32 v60, v60, v197
	v_sub_f32_e32 v67, v67, v197
	v_sub_f32_e32 v66, v66, v197
	v_sub_f32_e32 v65, v65, v197
	v_sub_f32_e32 v64, v64, v197
	v_sub_f32_e32 v87, v87, v197
	v_sub_f32_e32 v86, v86, v197
	v_sub_f32_e32 v85, v85, v197
	v_sub_f32_e32 v84, v84, v197
	s_branch .LBB0_875
.Lq1_o_bias2:
	v_add_u32_e32 v0, s87, v217
	v_add_u32_e32 v102, 0xc0, v0
	v_max_i32_e32 v3, -1, v102
	v_max_i32_e32 v124, -2, v102
	v_max_i32_e32 v125, -3, v102
	v_max_i32_e32 v126, -16, v102
	v_max_i32_e32 v127, 0xffffffef, v102
	v_max_i32_e32 v100, 0xffffffee, v102
	v_max_i32_e32 v101, 0xffffffed, v102
	v_add_u32_e32 v3, 1, v3
	v_add_u32_e32 v124, 2, v124
	v_add_u32_e32 v125, 3, v125
	v_add_u32_e32 v126, 16, v126
	v_add_u32_e32 v127, 17, v127
	v_add_u32_e32 v100, 18, v100
	v_add_u32_e32 v101, 19, v101
	v_med3_i32 v2, v102, 0, v209
	v_min_u32_e32 v3, 0xff, v3
	v_min_u32_e32 v124, 0xff, v124
	v_min_u32_e32 v125, 0xff, v125
	v_min_u32_e32 v126, 0xff, v126
	v_min_u32_e32 v127, 0xff, v127
	v_min_u32_e32 v100, 0xff, v100
	v_min_u32_e32 v101, 0xff, v101
	v_lshl_add_u32 v2, v2, 2, s71
	v_lshl_add_u32 v3, v3, 2, s71
	v_lshl_add_u32 v124, v124, 2, s71
	v_lshl_add_u32 v125, v125, 2, s71
	v_lshl_add_u32 v126, v126, 2, s71
	v_lshl_add_u32 v127, v127, 2, s71
	v_lshl_add_u32 v100, v100, 2, s71
	v_lshl_add_u32 v101, v101, 2, s71
	ds_read_b32 v2, v2
	ds_read_b32 v3, v3
	ds_read_b32 v124, v124
	ds_read_b32 v125, v125
	ds_read_b32 v126, v126
	ds_read_b32 v127, v127
	ds_read_b32 v100, v100
	ds_read_b32 v101, v101
	s_waitcnt lgkmcnt(4)
	v_pk_add_f32 v[130:131], v[130:131], v[124:125]
	v_pk_add_f32 v[128:129], v[128:129], v[2:3]
	v_max_i32_e32 v2, 0xffffffe0, v102
	v_max_i32_e32 v3, 0xffffffdf, v102
	v_max_i32_e32 v124, 0xffffffde, v102
	v_max_i32_e32 v125, 0xffffffdd, v102
	v_max_i32_e32 v103, 0xffffffd0, v102
	v_max_i32_e32 v116, 0xffffffcf, v102
	v_max_i32_e32 v117, 0xffffffce, v102
	v_add_u32_e32 v2, 32, v2
	v_add_u32_e32 v3, 33, v3
	v_add_u32_e32 v124, 34, v124
	v_add_u32_e32 v125, 35, v125
	v_add_u32_e32 v103, 48, v103
	v_add_u32_e32 v116, 49, v116
	v_add_u32_e32 v117, 50, v117
	v_max_i32_e32 v102, 0xffffffcd, v102
	v_min_u32_e32 v2, 0xff, v2
	v_min_u32_e32 v3, 0xff, v3
	v_min_u32_e32 v124, 0xff, v124
	v_min_u32_e32 v125, 0xff, v125
	v_min_u32_e32 v103, 0xff, v103
	v_min_u32_e32 v116, 0xff, v116
	v_min_u32_e32 v117, 0xff, v117
	v_add_u32_e32 v102, 51, v102
	v_lshl_add_u32 v2, v2, 2, s71
	v_lshl_add_u32 v3, v3, 2, s71
	v_lshl_add_u32 v124, v124, 2, s71
	v_lshl_add_u32 v125, v125, 2, s71
	v_lshl_add_u32 v103, v103, 2, s71
	v_lshl_add_u32 v116, v116, 2, s71
	v_lshl_add_u32 v117, v117, 2, s71
	v_min_u32_e32 v102, 0xff, v102
	v_lshl_add_u32 v118, v102, 2, s71
	ds_read_b32 v2, v2
	ds_read_b32 v3, v3
	ds_read_b32 v124, v124
	ds_read_b32 v125, v125
	ds_read_b32 v102, v103
	ds_read_b32 v103, v116
	ds_read_b32 v116, v117
	ds_read_b32 v117, v118
	v_add_u32_e32 v0, 0xb0, v0
	s_waitcnt lgkmcnt(8)
	v_pk_add_f32 v[38:39], v[38:39], v[100:101]
	v_pk_add_f32 v[36:37], v[36:37], v[126:127]
	s_waitcnt lgkmcnt(4)
	v_pk_add_f32 v[122:123], v[122:123], v[124:125]
	v_pk_add_f32 v[120:121], v[120:121], v[2:3]
	v_max_i32_e32 v3, -1, v0
	v_max_i32_e32 v124, -2, v0
	v_max_i32_e32 v125, -3, v0
	v_max_i32_e32 v126, -16, v0
	v_max_i32_e32 v127, 0xffffffef, v0
	v_max_i32_e32 v100, 0xffffffee, v0
	v_max_i32_e32 v101, 0xffffffed, v0
	v_add_u32_e32 v3, 1, v3
	v_add_u32_e32 v124, 2, v124
	v_add_u32_e32 v125, 3, v125
	v_add_u32_e32 v126, 16, v126
	v_add_u32_e32 v127, 17, v127
	v_add_u32_e32 v100, 18, v100
	v_add_u32_e32 v101, 19, v101
	v_med3_i32 v2, v0, 0, v209
	v_min_u32_e32 v3, 0xff, v3
	v_min_u32_e32 v124, 0xff, v124
	v_min_u32_e32 v125, 0xff, v125
	v_min_u32_e32 v126, 0xff, v126
	v_min_u32_e32 v127, 0xff, v127
	v_min_u32_e32 v100, 0xff, v100
	v_min_u32_e32 v101, 0xff, v101
	v_lshl_add_u32 v2, v2, 2, s71
	v_lshl_add_u32 v3, v3, 2, s71
	v_lshl_add_u32 v124, v124, 2, s71
	v_lshl_add_u32 v125, v125, 2, s71
	v_lshl_add_u32 v126, v126, 2, s71
	v_lshl_add_u32 v127, v127, 2, s71
	v_lshl_add_u32 v100, v100, 2, s71
	v_lshl_add_u32 v101, v101, 2, s71
	ds_read_b32 v2, v2
	ds_read_b32 v3, v3
	ds_read_b32 v124, v124
	ds_read_b32 v125, v125
	ds_read_b32 v126, v126
	ds_read_b32 v127, v127
	ds_read_b32 v100, v100
	ds_read_b32 v101, v101
	s_waitcnt lgkmcnt(8)
	v_pk_add_f32 v[42:43], v[42:43], v[116:117]
	v_pk_add_f32 v[40:41], v[40:41], v[102:103]
	s_waitcnt lgkmcnt(4)
	v_pk_add_f32 v[110:111], v[110:111], v[124:125]
	v_pk_add_f32 v[108:109], v[108:109], v[2:3]
	v_max_i32_e32 v2, 0xffffffe0, v0
	v_max_i32_e32 v3, 0xffffffdf, v0
	v_max_i32_e32 v124, 0xffffffde, v0
	v_max_i32_e32 v125, 0xffffffdd, v0
	v_max_i32_e32 v102, 0xffffffd0, v0
	v_max_i32_e32 v103, 0xffffffcf, v0
	v_max_i32_e32 v116, 0xffffffce, v0
	v_add_u32_e32 v2, 32, v2
	v_add_u32_e32 v3, 33, v3
	v_add_u32_e32 v124, 34, v124
	v_add_u32_e32 v125, 35, v125
	v_add_u32_e32 v102, 48, v102
	v_add_u32_e32 v103, 49, v103
	v_add_u32_e32 v116, 50, v116
	v_max_i32_e32 v0, 0xffffffcd, v0
	v_min_u32_e32 v2, 0xff, v2
	v_min_u32_e32 v3, 0xff, v3
	v_min_u32_e32 v124, 0xff, v124
	v_min_u32_e32 v125, 0xff, v125
	v_min_u32_e32 v102, 0xff, v102
	v_min_u32_e32 v103, 0xff, v103
	v_min_u32_e32 v116, 0xff, v116
	v_add_u32_e32 v0, 51, v0
	v_lshl_add_u32 v2, v2, 2, s71
	v_lshl_add_u32 v3, v3, 2, s71
	v_lshl_add_u32 v124, v124, 2, s71
	v_lshl_add_u32 v125, v125, 2, s71
	v_lshl_add_u32 v102, v102, 2, s71
	v_lshl_add_u32 v103, v103, 2, s71
	v_lshl_add_u32 v116, v116, 2, s71
	v_min_u32_e32 v0, 0xff, v0
	v_lshl_add_u32 v0, v0, 2, s71
	ds_read_b32 v2, v2
	ds_read_b32 v3, v3
	ds_read_b32 v124, v124
	ds_read_b32 v125, v125
	ds_read_b32 v102, v102
	ds_read_b32 v103, v103
	ds_read_b32 v116, v116
	ds_read_b32 v117, v0
	s_waitcnt lgkmcnt(8)
	v_pk_add_f32 v[62:63], v[62:63], v[100:101]
	v_pk_add_f32 v[60:61], v[60:61], v[126:127]
	s_waitcnt lgkmcnt(4)
	v_pk_add_f32 v[66:67], v[66:67], v[124:125]
	v_pk_add_f32 v[64:65], v[64:65], v[2:3]
	s_waitcnt lgkmcnt(0)
	v_pk_add_f32 v[86:87], v[86:87], v[116:117]
	v_pk_add_f32 v[84:85], v[84:85], v[102:103]
	s_branch .LBB0_877
.Lq1_o_resc2:
	s_mov_b32 s98, 1
	v_and_b32_e32 v124, 64, v212
	v_xor_b32_e32 v3, 16, v212
	v_add_u32_e32 v124, 64, v124
	v_cmp_lt_i32_e32 vcc, v3, v124
	v_xor_b32_e32 v125, 32, v212
	s_nop 0
	v_cndmask_b32_e32 v3, v212, v3, vcc
	v_lshlrev_b32_e32 v3, 2, v3
	ds_bpermute_b32 v126, v3, v0
	ds_bpermute_b32 v3, v3, v2
	v_cmp_lt_i32_e32 vcc, v125, v124
	v_max_f32_e32 v2, v2, v2
	v_max_f32_e32 v0, v0, v0
	v_cndmask_b32_e32 v124, v212, v125, vcc
	s_waitcnt lgkmcnt(0)
	v_max_f32_e32 v3, v3, v3
	v_lshlrev_b32_e32 v124, 2, v124
	v_max_f32_e32 v125, v126, v126
	v_max_f32_e32 v2, v2, v3
	v_max_f32_e32 v0, v0, v125
	ds_bpermute_b32 v3, v124, v2
	ds_bpermute_b32 v125, v124, v0
	s_waitcnt lgkmcnt(1)
	v_max_f32_e32 v3, v3, v3
	s_waitcnt lgkmcnt(0)
	v_max_f32_e32 v124, v125, v125
	v_max_f32_e32 v2, v2, v3
	v_max_f32_e32 v0, v0, v124
	v_cmp_lt_f32_e32 vcc, s74, v2
	s_nop 1
	v_cndmask_b32_e32 v3, 0, v2, vcc
	v_cmp_lt_f32_e32 vcc, s74, v0
	v_exp_f32_e64 v201, -v3
	v_sub_f32_e32 v108, v108, v3
	v_cndmask_b32_e32 v2, 0, v0, vcc
	v_exp_f32_e64 v200, -v2
	v_sub_f32_e32 v128, v128, v2
	v_sub_f32_e32 v129, v129, v2
	v_sub_f32_e32 v130, v130, v2
	v_sub_f32_e32 v131, v131, v2
	v_sub_f32_e32 v36, v36, v2
	v_sub_f32_e32 v37, v37, v2
	v_sub_f32_e32 v38, v38, v2
	v_sub_f32_e32 v39, v39, v2
	v_sub_f32_e32 v120, v120, v2
	v_sub_f32_e32 v121, v121, v2
	v_sub_f32_e32 v122, v122, v2
	v_sub_f32_e32 v123, v123, v2
	v_sub_f32_e32 v40, v40, v2
	v_sub_f32_e32 v41, v41, v2
	v_sub_f32_e32 v42, v42, v2
	v_sub_f32_e32 v43, v43, v2
	v_pk_add_f32 v[196:197], v[196:197], v[2:3]
	v_sub_f32_e32 v109, v109, v3
	v_sub_f32_e32 v110, v110, v3
	v_sub_f32_e32 v111, v111, v3
	v_sub_f32_e32 v60, v60, v3
	v_sub_f32_e32 v61, v61, v3
	v_sub_f32_e32 v62, v62, v3
	v_sub_f32_e32 v63, v63, v3
	v_sub_f32_e32 v64, v64, v3
	v_sub_f32_e32 v65, v65, v3
	v_sub_f32_e32 v66, v66, v3
	v_sub_f32_e32 v67, v67, v3
	v_sub_f32_e32 v84, v84, v3
	v_sub_f32_e32 v85, v85, v3
	v_sub_f32_e32 v86, v86, v3
	v_sub_f32_e32 v87, v87, v3
	v_pk_mul_f32 v[198:199], v[198:199], v[200:201]
	s_branch .LBB0_879
.Lq1_o_post2:
	v_mov_b32_e32 v0, v210
	s_nop 0
	v_lshlrev_b32_e32 v0, 2, v0
	v_and_b32_e32 v0, 60, v0
	v_and_or_b32 v0, v212, 64, v0
	v_lshlrev_b32_e32 v0, 2, v0
	ds_bpermute_b32 v188, v0, v200
	ds_bpermute_b32 v190, v0, v200 offset:8
	ds_bpermute_b32 v191, v0, v200 offset:12
	ds_bpermute_b32 v189, v0, v200 offset:4
	ds_bpermute_b32 v192, v0, v201
	ds_bpermute_b32 v194, v0, v201 offset:8
	ds_bpermute_b32 v195, v0, v201 offset:12
	ds_bpermute_b32 v193, v0, v201 offset:4
	s_waitcnt lgkmcnt(5)
	v_pk_mul_f32 v[130:131], v[130:131], v[190:191]
	s_waitcnt lgkmcnt(4)
	v_pk_mul_f32 v[128:129], v[128:129], v[188:189]
	v_pk_mul_f32 v[126:127], v[126:127], v[190:191]
	v_pk_mul_f32 v[124:125], v[124:125], v[188:189]
	v_pk_mul_f32 v[118:119], v[118:119], v[190:191]
	v_pk_mul_f32 v[116:117], v[116:117], v[188:189]
	v_pk_mul_f32 v[106:107], v[106:107], v[190:191]
	v_pk_mul_f32 v[104:105], v[104:105], v[188:189]
	v_pk_mul_f32 v[90:91], v[90:91], v[190:191]
	v_pk_mul_f32 v[88:89], v[88:89], v[188:189]
	v_pk_mul_f32 v[82:83], v[82:83], v[190:191]
	v_pk_mul_f32 v[80:81], v[80:81], v[188:189]
	v_pk_mul_f32 v[70:71], v[70:71], v[190:191]
	v_pk_mul_f32 v[68:69], v[68:69], v[188:189]
	v_pk_mul_f32 v[58:59], v[58:59], v[190:191]
	v_pk_mul_f32 v[56:57], v[56:57], v[188:189]
	s_waitcnt lgkmcnt(1)
	v_pk_mul_f32 v[122:123], v[122:123], v[194:195]
	s_waitcnt lgkmcnt(0)
	v_pk_mul_f32 v[120:121], v[120:121], v[192:193]
	v_pk_mul_f32 v[110:111], v[110:111], v[194:195]
	v_pk_mul_f32 v[108:109], v[108:109], v[192:193]
	v_pk_mul_f32 v[102:103], v[102:103], v[194:195]
	v_pk_mul_f32 v[100:101], v[100:101], v[192:193]
	v_pk_mul_f32 v[98:99], v[98:99], v[194:195]
	v_pk_mul_f32 v[96:97], v[96:97], v[192:193]
	v_pk_mul_f32 v[78:79], v[78:79], v[194:195]
	v_pk_mul_f32 v[76:77], v[76:77], v[192:193]
	v_pk_mul_f32 v[66:67], v[66:67], v[194:195]
	v_pk_mul_f32 v[64:65], v[64:65], v[192:193]
	v_pk_mul_f32 v[54:55], v[54:55], v[194:195]
	v_pk_mul_f32 v[52:53], v[52:53], v[192:193]
	v_pk_mul_f32 v[50:51], v[50:51], v[194:195]
	v_pk_mul_f32 v[48:49], v[48:49], v[192:193]
	s_branch .LBB0_881
